# MLA first tile: all twelve K-fragment LDS reads issued up front, QK^T MFMAs back to back behind counted lgkmcnt waits
# baseline (speedup 1.0000x reference)
.LBB0_477:
	v_lshrrev_b32_e32 v0, 1, v34
	v_lshlrev_b32_e32 v2, 3, v34
	v_bitop3_b32 v0, v0, v82, 1 bitop3:0x6c
	v_and_b32_e32 v83, 0x60, v2
	v_lshlrev_b32_e32 v84, 4, v0
	v_lshlrev_b32_e32 v0, 7, v34
	v_or_b32_e32 v35, v83, v0
	v_or_b32_e32 v185, v35, v84
	v_add_u32_e32 v6, 0, v185
	v_xad_u32 v40, v185, 32, 0
	v_xad_u32 v44, v185, 64, 0
	s_movk_i32 s59, 0x60
	v_bitop3_b32 v35, v35, s59, v84 bitop3:0x36
	v_add_u32_e32 v35, 0, v35
	v_lshlrev_b32_e32 v85, 6, v34
	v_lshlrev_b32_e32 v182, 2, v82
	s_cmp_gt_i32 s10, 62
	ds_read_b128 v[2:5], v6
	ds_read_b128 v[18:21], v6 offset:4096
	ds_read_b128 v[36:39], v40
	ds_read_b128 v[202:205], v40 offset:4096
	ds_read_b128 v[206:209], v44
	ds_read_b128 v[210:213], v44 offset:4096
	ds_read_b128 v[214:217], v35
	ds_read_b128 v[218:221], v35 offset:4096
	v_lshrrev_b32_e32 v35, 2, v34
	v_lshlrev_b32_e32 v34, 2, v34
	v_and_b32_e32 v86, 32, v34
	v_bitop3_b32 v34, v35, v82, 1 bitop3:0x6c
	v_lshlrev_b32_e32 v87, 4, v34
	v_or3_b32 v183, v86, v85, v87
	v_add_u32_e32 v184, 0, v183
	v_xad_u32 v42, v183, 32, 0
	ds_read_b128 v[222:225], v184 offset:8192
	ds_read_b128 v[58:61], v184 offset:10240
	ds_read_b128 v[62:65], v42 offset:8192
	ds_read_b128 v[66:69], v42 offset:10240
	s_waitcnt lgkmcnt(11)
	v_mfma_f32_32x32x16_bf16 v[2:17], v[2:5], v[134:137], 0
	s_waitcnt lgkmcnt(10)
	v_mfma_f32_32x32x16_bf16 v[18:33], v[18:21], v[134:137], 0
	s_waitcnt lgkmcnt(9)
	v_mfma_f32_32x32x16_bf16 v[2:17], v[36:39], v[130:133], v[2:17]
	s_waitcnt lgkmcnt(8)
	v_mfma_f32_32x32x16_bf16 v[18:33], v[202:205], v[130:133], v[18:33]
	s_waitcnt lgkmcnt(7)
	v_mfma_f32_32x32x16_bf16 v[2:17], v[206:209], v[126:129], v[2:17]
	s_waitcnt lgkmcnt(6)
	v_mfma_f32_32x32x16_bf16 v[18:33], v[210:213], v[126:129], v[18:33]
	s_waitcnt lgkmcnt(5)
	v_mfma_f32_32x32x16_bf16 v[2:17], v[214:217], v[122:125], v[2:17]
	s_waitcnt lgkmcnt(4)
	v_mfma_f32_32x32x16_bf16 v[18:33], v[218:221], v[122:125], v[18:33]
	s_waitcnt lgkmcnt(3)
	v_mfma_f32_32x32x16_bf16 v[2:17], v[222:225], v[118:121], v[2:17]
	s_waitcnt lgkmcnt(2)
	v_mfma_f32_32x32x16_bf16 v[18:33], v[58:61], v[118:121], v[18:33]
	s_waitcnt lgkmcnt(1)
	v_mfma_f32_32x32x16_bf16 v[2:17], v[62:65], v[114:117], v[2:17]
	s_waitcnt lgkmcnt(0)
	v_mfma_f32_32x32x16_bf16 v[18:33], v[66:69], v[114:117], v[18:33]
	s_cbranch_scc1 .LBB0_479
	v_or_b32_e32 v34, 32, v182
	v_cmp_le_i32_e32 vcc, v34, v172
	v_or_b32_e32 v34, 33, v182
	s_nop 7
	v_cndmask_b32_e32 v18, v177, v18, vcc
	v_cmp_lt_i32_e32 vcc, v182, v172
	s_nop 1
	v_cndmask_b32_e32 v3, v177, v3, vcc
	v_cmp_le_i32_e32 vcc, v182, v172
	s_nop 1
	v_cndmask_b32_e32 v2, v177, v2, vcc
	v_cmp_le_i32_e32 vcc, v34, v172
	v_or_b32_e32 v34, 2, v182
	s_nop 0
	v_cndmask_b32_e32 v19, v177, v19, vcc
	v_cmp_le_i32_e32 vcc, v34, v172
	v_or_b32_e32 v34, 34, v182
	s_nop 0
	v_cndmask_b32_e32 v4, v177, v4, vcc
	v_cmp_le_i32_e32 vcc, v34, v172
	v_or_b32_e32 v34, 3, v182
	s_nop 0
	v_cndmask_b32_e32 v20, v177, v20, vcc
	v_cmp_le_i32_e32 vcc, v34, v172
	v_or_b32_e32 v34, 35, v182
	s_nop 0
	v_cndmask_b32_e32 v5, v177, v5, vcc
	v_cmp_le_i32_e32 vcc, v34, v172
	v_or_b32_e32 v34, 8, v182
	s_nop 0
	v_cndmask_b32_e32 v21, v177, v21, vcc
	v_cmp_le_i32_e32 vcc, v34, v172
	v_or_b32_e32 v34, 40, v182
	s_nop 0
	v_cndmask_b32_e32 v6, v177, v6, vcc
	v_cmp_le_i32_e32 vcc, v34, v172
	v_or_b32_e32 v34, 9, v182
	s_nop 0
	v_cndmask_b32_e32 v22, v177, v22, vcc
	v_cmp_le_i32_e32 vcc, v34, v172
	v_or_b32_e32 v34, 41, v182
	s_nop 0
	v_cndmask_b32_e32 v7, v177, v7, vcc
	v_cmp_le_i32_e32 vcc, v34, v172
	v_or_b32_e32 v34, 10, v182
	s_nop 0
	v_cndmask_b32_e32 v23, v177, v23, vcc
	v_cmp_le_i32_e32 vcc, v34, v172
	v_or_b32_e32 v34, 42, v182
	s_nop 0
	v_cndmask_b32_e32 v8, v177, v8, vcc
	v_cmp_le_i32_e32 vcc, v34, v172
	v_or_b32_e32 v34, 11, v182
	s_nop 0
	v_cndmask_b32_e32 v24, v177, v24, vcc
	v_cmp_le_i32_e32 vcc, v34, v172
	v_or_b32_e32 v34, 43, v182
	s_nop 0
	v_cndmask_b32_e32 v9, v177, v9, vcc
	v_cmp_le_i32_e32 vcc, v34, v172
	v_or_b32_e32 v34, 16, v182
	s_nop 0
	v_cndmask_b32_e32 v25, v177, v25, vcc
	v_cmp_le_i32_e32 vcc, v34, v172
	v_or_b32_e32 v34, 48, v182
	s_nop 0
	v_cndmask_b32_e32 v10, v177, v10, vcc
	v_cmp_le_i32_e32 vcc, v34, v172
	v_or_b32_e32 v34, 17, v182
	s_nop 0
	v_cndmask_b32_e32 v26, v177, v26, vcc
	v_cmp_le_i32_e32 vcc, v34, v172
	v_or_b32_e32 v34, 49, v182
	s_nop 0
	v_cndmask_b32_e32 v11, v177, v11, vcc
	v_cmp_le_i32_e32 vcc, v34, v172
	v_or_b32_e32 v34, 18, v182
	s_nop 0
	v_cndmask_b32_e32 v27, v177, v27, vcc
	v_cmp_le_i32_e32 vcc, v34, v172
	v_or_b32_e32 v34, 50, v182
	s_nop 0
	v_cndmask_b32_e32 v12, v177, v12, vcc
	v_cmp_le_i32_e32 vcc, v34, v172
	v_or_b32_e32 v34, 19, v182
	s_nop 0
	v_cndmask_b32_e32 v28, v177, v28, vcc
	v_cmp_le_i32_e32 vcc, v34, v172
	v_or_b32_e32 v34, 51, v182
	s_nop 0
	v_cndmask_b32_e32 v13, v177, v13, vcc
	v_cmp_le_i32_e32 vcc, v34, v172
	v_or_b32_e32 v34, 24, v182
	s_nop 0
	v_cndmask_b32_e32 v29, v177, v29, vcc
	v_cmp_le_i32_e32 vcc, v34, v172
	v_or_b32_e32 v34, 56, v182
	s_nop 0
	v_cndmask_b32_e32 v14, v177, v14, vcc
	v_cmp_le_i32_e32 vcc, v34, v172
	v_or_b32_e32 v34, 25, v182
	s_nop 0
	v_cndmask_b32_e32 v30, v177, v30, vcc
	v_cmp_le_i32_e32 vcc, v34, v172
	v_or_b32_e32 v34, 57, v182
	s_nop 0
	v_cndmask_b32_e32 v15, v177, v15, vcc
	v_cmp_le_i32_e32 vcc, v34, v172
	v_or_b32_e32 v34, 26, v182
	s_nop 0
	v_cndmask_b32_e32 v31, v177, v31, vcc
	v_cmp_le_i32_e32 vcc, v34, v172
	v_or_b32_e32 v34, 58, v182
	s_nop 0
	v_cndmask_b32_e32 v16, v177, v16, vcc
	v_cmp_le_i32_e32 vcc, v34, v172
	v_or_b32_e32 v34, 27, v182
	s_nop 0
	v_cndmask_b32_e32 v32, v177, v32, vcc
	v_cmp_le_i32_e32 vcc, v34, v172
	v_or_b32_e32 v34, 59, v182
	s_nop 0
	v_cndmask_b32_e32 v17, v177, v17, vcc
	v_cmp_le_i32_e32 vcc, v34, v172
	s_nop 1
	v_cndmask_b32_e32 v33, v177, v33, vcc
